# MLA loop: wave halves staggered (waves 0-3 run a clone whose per-tile barrier and stage DMA sit after MFMA 18 of step A; waves 4-7 unchanged behind one entry barrier)
# speedup vs baseline: 1.0272x; 1.0272x over previous
.LBB0_849:
	s_cmpk_gt_i32 s2, 0x207
	s_cbranch_scc1 .LBB0_885
	v_lshlrev_b32_e32 v3, 3, v0
	v_lshrrev_b32_e32 v4, 5, v1
	v_and_b32_e32 v1, 8, v3
	v_and_b32_e32 v2, 31, v0
	v_or_b32_e32 v3, v1, v4
	v_bfe_u32 v5, v0, 1, 4
	v_mov_b32_e32 v10, 0x12000
	v_and_b32_e32 v11, 19, v0
	v_lshlrev_b32_e32 v0, 1, v0
	v_bitop3_b32 v6, v3, v5, 6 bitop3:0x36
	v_bitop3_b32 v7, v3, v5, 4 bitop3:0x36
	v_bitop3_b32 v8, v3, v5, 2 bitop3:0x36
	v_bitop3_b32 v9, v1, v5, v4 bitop3:0x36
	v_lshl_or_b32 v10, v5, 8, v10
	v_and_b32_e32 v5, 4, v5
	v_and_b32_e32 v0, 8, v0
	v_or3_b32 v0, v5, v0, v11
	v_lshrrev_b32_e32 v5, 1, v0
	v_bitop3_b32 v1, v5, v1, v4 bitop3:0x1e
	v_lshlrev_b32_e32 v13, 4, v1
	v_or_b32_e32 v1, 14, v4
	s_load_dwordx2 s[34:35], s[8:9], 0xf8
	v_bitop3_b32 v14, v0, v1, 15 bitop3:0x6c
	v_or_b32_e32 v1, 12, v4
	v_bitop3_b32 v15, v0, v1, 15 bitop3:0x6c
	v_or_b32_e32 v1, 10, v4
	v_bitop3_b32 v16, v0, v1, 15 bitop3:0x6c
	v_or_b32_e32 v1, 8, v4
	v_bitop3_b32 v17, v0, v1, 15 bitop3:0x6c
	v_or_b32_e32 v1, 6, v4
	v_bitop3_b32 v18, v0, v1, 15 bitop3:0x6c
	v_or_b32_e32 v1, 4, v4
	s_waitcnt lgkmcnt(0)
	s_add_u32 s3, s34, 0x140f0000
	v_bitop3_b32 v19, v0, v1, 15 bitop3:0x6c
	v_or_b32_e32 v1, 2, v4
	v_lshlrev_b32_e32 v186, 4, v4
	v_mov_b32_e32 v187, 0
	s_addc_u32 s38, s35, 0
	v_bitop3_b32 v20, v0, v1, 15 bitop3:0x6c
	v_bitop3_b32 v21, v0, v4, 15 bitop3:0x6c
	v_lshlrev_b32_e32 v22, 8, v0
	v_lshl_add_u64 v[0:1], s[34:35], 0, v[186:187]
	s_mov_b64 s[8:9], 0x11030000
	s_add_u32 s39, s34, 0x171b0000
	v_lshl_add_u64 v[188:189], v[0:1], 0, s[8:9]
	v_lshlrev_b32_e32 v0, 2, v4
	s_addc_u32 s40, s35, 0
	v_bitop3_b32 v11, v5, v3, 6 bitop3:0x1e
	v_bitop3_b32 v12, v5, v3, 4 bitop3:0x1e
	v_bitop3_b32 v3, v5, v3, 2 bitop3:0x1e
	v_lshlrev_b32_e32 v186, 1, v0
	v_mbcnt_lo_u32_b32 v0, -1, 0
	s_add_u32 s36, s34, 0xc300000
	v_lshlrev_b32_e32 v11, 4, v11
	v_lshlrev_b32_e32 v12, 4, v12
	v_lshlrev_b32_e32 v3, 4, v3
	v_lshlrev_b32_e32 v5, 8, v5
	v_mbcnt_hi_u32_b32 v222, -1, v0
	s_addc_u32 s37, s35, 0
	v_lshl_or_b32 v204, s12, 5, v2
	v_mov_b32_e32 v177, v187
	s_add_i32 s41, s14, 0
	v_mov_b32_e32 v179, v187
	s_add_i32 s42, s16, 0
	v_mov_b32_e32 v181, v187
	s_add_i32 s43, s18, 0
	v_mov_b32_e32 v183, v187
	s_add_i32 s44, s20, 0
	v_mov_b32_e32 v185, v187
	s_add_i32 s45, s22, 0
	v_lshl_add_u32 v1, v21, 4, 0
	v_lshl_add_u32 v2, v20, 4, 0
	v_lshl_add_u32 v4, v19, 4, 0
	v_lshl_add_u32 v18, v18, 4, 0
	v_lshl_add_u32 v17, v17, 4, 0
	v_lshl_add_u32 v16, v16, 4, 0
	v_lshl_add_u32 v15, v15, 4, 0
	v_lshl_add_u32 v14, v14, 4, 0
	v_add3_u32 v205, 0, v13, v5
	v_add3_u32 v207, 0, v3, v5
	v_add3_u32 v209, 0, v12, v5
	v_add3_u32 v211, 0, v11, v5
	v_lshl_add_u32 v3, v9, 4, 0
	v_lshl_add_u32 v5, v8, 4, 0
	s_lshl_b32 s4, s13, 1
	s_lshl_b32 s5, s15, 1
	s_lshl_b32 s8, s17, 1
	s_lshl_b32 s9, s19, 1
	s_lshl_b32 s10, s21, 1
	v_lshl_add_u32 v7, v7, 4, 0
	v_lshl_add_u32 v6, v6, 4, 0
	v_and_b32_e32 v0, 64, v222
	v_add_u32_e32 v206, 0xc000, v205
	v_add_u32_e32 v208, 0xc000, v207
	v_add_u32_e32 v210, 0xc000, v209
	v_add_u32_e32 v212, 0xc000, v211
	s_add_i32 s46, s41, s13
	s_add_i32 s47, s42, s15
	s_add_i32 s48, s43, s17
	s_add_i32 s49, s44, s19
	s_add_i32 s50, s45, s21
	v_mov_b32_e32 v213, 0x4100
	s_movk_i32 s51, 0x180
	v_lshlrev_b64 v[190:191], 1, v[176:177]
	v_lshlrev_b64 v[192:193], 1, v[178:179]
	v_lshlrev_b64 v[194:195], 1, v[180:181]
	v_lshlrev_b64 v[196:197], 1, v[182:183]
	s_add_i32 s52, s41, s4
	s_add_i32 s53, s42, s5
	s_add_i32 s54, s43, s8
	s_add_i32 s55, s44, s9
	s_add_i32 s56, s45, s10
	v_lshlrev_b64 v[198:199], 1, v[184:185]
	v_add_u32_e32 v214, v1, v22
	v_add_u32_e32 v215, v2, v22
	v_add_u32_e32 v216, v4, v22
	v_add_u32_e32 v217, v18, v22
	v_add_u32_e32 v218, v17, v22
	v_add_u32_e32 v219, v16, v22
	v_add_u32_e32 v220, v15, v22
	v_add_u32_e32 v221, v14, v22
	v_xor_b32_e32 v223, 32, v222
	v_add_u32_e32 v224, 64, v0
	v_add_u32_e32 v225, v3, v10
	v_add_u32_e32 v226, v5, v10
	v_add_u32_e32 v227, v7, v10
	v_add_u32_e32 v228, v6, v10
	v_lshrrev_b32_e32 v234, 8, v202
	s_nop 0
	v_readfirstlane_b32 s96, v234
	s_mov_b32 s57, s2
	s_branch .LBB0_853

.LBB0_857:
	v_lshl_add_u32 v200, s63, 8, v204
	v_ashrrev_i32_e32 v201, 31, v200
	v_mad_i64_i32 v[0:1], s[20:21], s58, v213, v[200:201]
	v_mad_u64_u32 v[2:3], s[20:21], v0, s51, v[188:189]
	v_mad_i32_i24 v3, v1, s51, v3
	global_load_dwordx4 v[144:147], v[2:3], off
	global_load_dwordx4 v[156:159], v[2:3], off offset:32
	global_load_dwordx4 v[168:171], v[2:3], off offset:64
	global_load_dwordx4 v[172:175], v[2:3], off offset:96
	global_load_dwordx4 v[164:167], v[2:3], off offset:128
	global_load_dwordx4 v[160:163], v[2:3], off offset:160
	global_load_dwordx4 v[152:155], v[2:3], off offset:192
	global_load_dwordx4 v[148:151], v[2:3], off offset:224
	global_load_dwordx4 v[140:143], v[2:3], off offset:256
	global_load_dwordx4 v[136:139], v[2:3], off offset:288
	global_load_dwordx4 v[132:135], v[2:3], off offset:320
	global_load_dwordx4 v[128:131], v[2:3], off offset:352
	s_mul_i32 s60, s58, 0x618000
	s_mul_hi_i32 s59, s58, 0x618000
	s_add_u32 s4, s3, s60
	s_mul_i32 s62, s58, 0x410000
	s_addc_u32 s5, s38, s59
	s_mul_hi_i32 s61, s58, 0x410000
	s_add_u32 s9, s39, s62
	s_addc_u32 s22, s40, s61
	s_and_b64 s[10:11], s[24:25], exec
	s_cselect_b32 s10, s9, s4
	s_cselect_b32 s11, s22, s5
	s_and_b64 s[12:13], s[26:27], exec
	s_cselect_b32 s12, s9, s4
	s_cselect_b32 s13, s22, s5
	s_and_b64 s[14:15], s[28:29], exec
	s_cselect_b32 s14, s9, s4
	s_cselect_b32 s15, s22, s5
	s_and_b64 s[16:17], s[30:31], exec
	s_cselect_b32 s16, s9, s4
	s_cselect_b32 s17, s22, s5
	s_and_b64 s[18:19], s[6:7], exec
	s_cselect_b32 s18, s9, s4
	s_cselect_b32 s19, s22, s5
	s_add_u32 s4, s4, 0x6000
	s_mov_b32 m0, s41
	s_addc_u32 s5, s5, 0
	v_lshl_add_u64 v[0:1], s[10:11], 0, v[190:191]
	s_add_u32 s9, s9, 0x80
	global_load_lds_dwordx4 v[0:1], off
	v_lshl_add_u64 v[0:1], s[12:13], 0, v[192:193]
	s_mov_b32 m0, s42
	s_addc_u32 s80, s22, 0
	global_load_lds_dwordx4 v[0:1], off
	v_lshl_add_u64 v[0:1], s[14:15], 0, v[194:195]
	s_mov_b32 m0, s43
	s_and_b64 s[20:21], s[24:25], exec
	global_load_lds_dwordx4 v[0:1], off
	v_lshl_add_u64 v[0:1], s[16:17], 0, v[196:197]
	s_mov_b32 m0, s44
	s_cselect_b32 s20, s9, s4
	s_cselect_b32 s21, s80, s5
	s_and_b64 s[22:23], s[26:27], exec
	global_load_lds_dwordx4 v[0:1], off
	v_lshl_add_u64 v[0:1], s[18:19], 0, v[198:199]
	s_mov_b32 m0, s45
	s_cselect_b32 s22, s9, s4
	s_cselect_b32 s23, s80, s5
	s_and_b64 s[74:75], s[28:29], exec
	global_load_lds_dwordx4 v[0:1], off
	v_lshl_add_u64 v[0:1], s[20:21], 0, v[190:191]
	s_mov_b32 m0, s46
	s_cselect_b32 s74, s9, s4
	s_cselect_b32 s75, s80, s5
	s_and_b64 s[76:77], s[30:31], exec
	global_load_lds_dwordx4 v[0:1], off
	v_lshl_add_u64 v[0:1], s[22:23], 0, v[192:193]
	s_mov_b32 m0, s47
	s_cselect_b32 s76, s9, s4
	s_cselect_b32 s77, s80, s5
	s_and_b64 s[78:79], s[6:7], exec
	global_load_lds_dwordx4 v[0:1], off
	v_lshl_add_u64 v[0:1], s[74:75], 0, v[194:195]
	s_mov_b32 m0, s48
	s_cselect_b32 s78, s9, s4
	s_cselect_b32 s79, s80, s5
	global_load_lds_dwordx4 v[0:1], off
	v_lshl_add_u64 v[0:1], s[76:77], 0, v[196:197]
	s_mov_b32 m0, s49
	v_cmp_lt_i32_e32 vcc, v223, v224
	global_load_lds_dwordx4 v[0:1], off
	v_lshl_add_u64 v[0:1], s[78:79], 0, v[198:199]
	s_mov_b32 m0, s50
	v_cndmask_b32_e32 v16, v222, v223, vcc
	global_load_lds_dwordx4 v[0:1], off
	s_waitcnt vmcnt(0)
	s_barrier
	ds_read_b128 v[0:3], v214
	ds_read_b128 v[4:7], v215
	s_waitcnt vmcnt(0) lgkmcnt(0)
	v_mfma_f32_32x32x16_bf16 v[66:81], v[0:3], v[144:147], 0
	v_lshlrev_b32_e32 v229, 2, v16
	s_mov_b32 s9, s8
	s_mov_b32 s10, s8
	s_mov_b32 s11, s8
	s_mov_b32 s12, s8
	s_mov_b32 s13, s8
	s_mov_b32 s14, s8
	v_mfma_f32_32x32x16_bf16 v[66:81], v[4:7], v[156:159], v[66:81]
	ds_read_b128 v[0:3], v216
	ds_read_b128 v[4:7], v217
	s_mov_b32 s15, s8
	s_mov_b32 s16, s8
	s_mov_b32 s17, s8
	s_mov_b32 s18, s8
	s_mov_b32 s19, s8
	s_mov_b32 s20, s8
	s_waitcnt lgkmcnt(1)
	v_mfma_f32_32x32x16_bf16 v[66:81], v[0:3], v[168:171], v[66:81]
	s_mov_b32 s21, s8
	s_mov_b32 s22, s8
	s_mov_b32 s23, s8
	s_cmp_eq_u32 s63, 0
	v_mov_b32_e32 v82, 0
	v_mov_b32_e32 v230, 0
	s_waitcnt lgkmcnt(0)
	v_mfma_f32_32x32x16_bf16 v[66:81], v[4:7], v[172:175], v[66:81]
	ds_read_b128 v[0:3], v218
	ds_read_b128 v[4:7], v219
	s_waitcnt lgkmcnt(1)
	v_mfma_f32_32x32x16_bf16 v[66:81], v[0:3], v[164:167], v[66:81]
	s_waitcnt lgkmcnt(0)
	v_mfma_f32_32x32x16_bf16 v[66:81], v[4:7], v[160:163], v[66:81]
	ds_read_b128 v[0:3], v220
	ds_read_b128 v[4:7], v221
	ds_read_b128 v[32:35], v212
	s_waitcnt lgkmcnt(2)
	v_mfma_f32_32x32x16_bf16 v[66:81], v[0:3], v[152:155], v[66:81]
	ds_read_b128 v[0:3], v206
	s_waitcnt lgkmcnt(2)
	v_mfma_f32_32x32x16_bf16 v[66:81], v[4:7], v[148:151], v[66:81]
	ds_read_b128 v[4:7], v208
	s_waitcnt lgkmcnt(1)
	v_mfma_f32_32x32x16_bf16 v[66:81], v[0:3], v[140:143], v[66:81]
	ds_read_b128 v[0:3], v210
	s_waitcnt lgkmcnt(1)
	v_mfma_f32_32x32x16_bf16 v[66:81], v[4:7], v[136:139], v[66:81]
	s_waitcnt lgkmcnt(0)
	v_mfma_f32_32x32x16_bf16 v[66:81], v[0:3], v[132:135], v[66:81]
	v_mov_b64_e32 v[0:1], s[8:9]
	v_mov_b64_e32 v[14:15], s[22:23]
	v_mov_b64_e32 v[2:3], s[10:11]
	v_mov_b64_e32 v[4:5], s[12:13]
	v_mov_b64_e32 v[6:7], s[14:15]
	v_mov_b64_e32 v[8:9], s[16:17]
	v_mov_b64_e32 v[10:11], s[18:19]
	v_mfma_f32_32x32x16_bf16 v[66:81], v[32:35], v[128:131], v[66:81]
	v_mov_b64_e32 v[12:13], s[20:21]
	v_mov_b64_e32 v[30:31], v[14:15]
	v_mov_b64_e32 v[62:63], v[14:15]
	v_mov_b64_e32 v[28:29], v[12:13]
	v_mov_b64_e32 v[26:27], v[10:11]
	v_mov_b64_e32 v[24:25], v[8:9]
	v_mov_b64_e32 v[22:23], v[6:7]
	s_nop 4
	v_max_f32_e32 v32, v67, v67
	v_max_f32_e32 v33, v66, v66
	v_max_f32_e32 v32, v33, v32
	v_max3_f32 v32, v32, v68, v69
	v_max3_f32 v32, v32, v70, v71
	v_max3_f32 v32, v32, v72, v73
	v_max3_f32 v32, v32, v74, v75
	v_max3_f32 v32, v32, v76, v77
	v_max3_f32 v32, v32, v78, v79
	v_max3_f32 v64, v32, v80, v81
	ds_bpermute_b32 v65, v229, v64
	v_mov_b64_e32 v[46:47], v[14:15]
	v_mov_b64_e32 v[20:21], v[4:5]
	v_mov_b64_e32 v[18:19], v[2:3]
	v_mov_b64_e32 v[16:17], v[0:1]
	s_waitcnt lgkmcnt(0)
	v_max_f32_e32 v65, v65, v65
	v_max_f32_e32 v65, v64, v65
	v_xor_b32_e32 v64, 0x80000000, v65
	v_mov_b64_e32 v[44:45], v[12:13]
	v_mov_b64_e32 v[42:43], v[10:11]
	v_mov_b64_e32 v[40:41], v[8:9]
	v_mov_b64_e32 v[38:39], v[6:7]
	v_mov_b64_e32 v[36:37], v[4:5]
	v_mov_b64_e32 v[34:35], v[2:3]
	v_mov_b64_e32 v[32:33], v[0:1]
	v_mov_b64_e32 v[60:61], v[12:13]
	v_mov_b64_e32 v[58:59], v[10:11]
	v_mov_b64_e32 v[56:57], v[8:9]
	v_mov_b64_e32 v[54:55], v[6:7]
	v_mov_b64_e32 v[52:53], v[4:5]
	v_mov_b64_e32 v[50:51], v[2:3]
	v_mov_b64_e32 v[48:49], v[0:1]
	s_cselect_b32 s9, 4, 0x104
	v_sub_f32_e32 v111, v81, v65
	v_sub_f32_e32 v110, v80, v65
	v_sub_f32_e32 v109, v79, v65
	v_sub_f32_e32 v108, v78, v65
	v_sub_f32_e32 v107, v77, v65
	v_sub_f32_e32 v106, v76, v65
	v_sub_f32_e32 v105, v75, v65
	v_sub_f32_e32 v104, v74, v65
	v_sub_f32_e32 v103, v73, v65
	v_sub_f32_e32 v102, v72, v65
	v_sub_f32_e32 v101, v71, v65
	v_sub_f32_e32 v100, v70, v65
	v_sub_f32_e32 v99, v69, v65
	v_sub_f32_e32 v98, v68, v65
	v_sub_f32_e32 v97, v67, v65
	v_sub_f32_e32 v96, v66, v65
	v_mov_b32_e32 v65, v64
	v_mov_b32_e32 v66, v64
	v_mov_b32_e32 v67, v64
	v_mov_b32_e32 v68, v64
	v_mov_b32_e32 v69, v64
	v_mov_b32_e32 v70, v64
	v_mov_b32_e32 v71, v64
	v_mov_b32_e32 v72, v64
	v_mov_b32_e32 v73, v64
	v_mov_b32_e32 v74, v64
	v_mov_b32_e32 v75, v64
	v_mov_b32_e32 v76, v64
	v_mov_b32_e32 v77, v64
	v_mov_b32_e32 v78, v64
	v_mov_b32_e32 v79, v64
	s_cmp_eq_u32 s96, 0
	s_cbranch_scc1 .Lmla_ld_entry
	s_barrier
	v_cmp_lt_f32_e32 vcc, 0, v82
	s_cbranch_vccz .LBB0_859

.Lmla_ld_entry:
	v_cmp_lt_f32_e32 vcc, 0, v82
	s_cbranch_vccz .LBB0_859_ld

.LBB0_859_ld:
	ds_read_b128 v[236:239], v214 offset:8192
	ds_read_b128 v[240:243], v215 offset:8192
	ds_read_b128 v[244:247], v216 offset:8192
	ds_read_b128 v[248:251], v217 offset:8192
	v_exp_f32_e32 v97, v97
	v_exp_f32_e32 v99, v99
	v_exp_f32_e32 v100, v100
	v_exp_f32_e32 v101, v101
	v_exp_f32_e32 v102, v102
	v_exp_f32_e32 v103, v103
	v_exp_f32_e32 v106, v106
	v_exp_f32_e32 v107, v107
	s_waitcnt lgkmcnt(3)
	v_mfma_f32_32x32x16_bf16 v[80:95], v[236:239], v[144:147], v[64:79]
	ds_read_b128 v[252:255], v218 offset:8192
	v_exp_f32_e32 v108, v108
	v_exp_f32_e32 v109, v109
	v_exp_f32_e32 v110, v110
	v_exp_f32_e32 v111, v111
	s_waitcnt lgkmcnt(3)
	v_mfma_f32_32x32x16_bf16 v[80:95], v[240:243], v[156:159], v[80:95]
	ds_read_b128 v[236:239], v219 offset:8192
	s_waitcnt lgkmcnt(3)
	v_mfma_f32_32x32x16_bf16 v[80:95], v[244:247], v[168:171], v[80:95]
	ds_read_b128 v[240:243], v220 offset:8192
	s_waitcnt lgkmcnt(3)
	v_mfma_f32_32x32x16_bf16 v[80:95], v[248:251], v[172:175], v[80:95]
	ds_read_b128 v[244:247], v221 offset:8192
	s_waitcnt lgkmcnt(3)
	v_mfma_f32_32x32x16_bf16 v[80:95], v[252:255], v[164:167], v[80:95]
	ds_read_b128 v[248:251], v205 offset:53248
	s_waitcnt lgkmcnt(3)
	v_mfma_f32_32x32x16_bf16 v[80:95], v[236:239], v[160:163], v[80:95]
	ds_read_b128 v[252:255], v207 offset:53248
	s_waitcnt lgkmcnt(3)
	v_mfma_f32_32x32x16_bf16 v[80:95], v[240:243], v[152:155], v[80:95]
	ds_read_b128 v[236:239], v209 offset:53248
	s_waitcnt lgkmcnt(3)
	v_mfma_f32_32x32x16_bf16 v[80:95], v[244:247], v[148:151], v[80:95]
	ds_read_b128 v[240:243], v211 offset:53248
	s_waitcnt lgkmcnt(3)
	v_mfma_f32_32x32x16_bf16 v[80:95], v[248:251], v[140:143], v[80:95]
	ds_read_b128 v[244:247], v225
	s_waitcnt lgkmcnt(3)
	v_mfma_f32_32x32x16_bf16 v[80:95], v[252:255], v[136:139], v[80:95]
	ds_read_b128 v[248:251], v225 offset:4096
	s_waitcnt lgkmcnt(3)
	v_mfma_f32_32x32x16_bf16 v[80:95], v[236:239], v[132:135], v[80:95]
	ds_read_b128 v[252:255], v225 offset:8192
	s_waitcnt lgkmcnt(3)
	v_mfma_f32_32x32x16_bf16 v[80:95], v[240:243], v[128:131], v[80:95]
	ds_read_b128 v[236:239], v225 offset:12288
	v_exp_f32_e32 v112, v96
	v_exp_f32_e32 v113, v98
	v_exp_f32_e32 v114, v104
	v_exp_f32_e32 v115, v105
	v_add_f32_e32 v96, 0, v112
	v_add_f32_e32 v96, v97, v96
	v_add_f32_e32 v96, v113, v96
	v_add_f32_e32 v96, v99, v96
	v_add_f32_e32 v96, v100, v96
	v_add_f32_e32 v96, v101, v96
	v_add_f32_e32 v96, v102, v96
	v_add_f32_e32 v96, v103, v96
	v_cvt_pk_bf16_f32 v100, v100, v101
	v_cvt_pk_bf16_f32 v101, v102, v103
	v_cvt_pk_bf16_f32 v98, v112, v97
	v_cvt_pk_bf16_f32 v99, v113, v99
	v_max_f32_e32 v97, v81, v81
	v_add_f32_e32 v96, v114, v96
	s_waitcnt lgkmcnt(3)
	v_mfma_f32_32x32x16_bf16 v[48:63], v[244:247], v[98:101], v[48:63]
	ds_read_b128 v[240:243], v226
	v_add_f32_e32 v96, v115, v96
	v_add_f32_e32 v96, v106, v96
	v_add_f32_e32 v96, v107, v96
	v_add_f32_e32 v96, v108, v96
	v_add_f32_e32 v96, v109, v96
	v_add_f32_e32 v96, v110, v96
	s_waitcnt lgkmcnt(3)
	v_mfma_f32_32x32x16_bf16 v[32:47], v[248:251], v[98:101], v[32:47]
	ds_read_b128 v[244:247], v226 offset:4096
	v_add_f32_e32 v96, v111, v96
	v_add_f32_e32 v112, v230, v96
	s_waitcnt lgkmcnt(3)
	v_mfma_f32_32x32x16_bf16 v[16:31], v[252:255], v[98:101], v[16:31]
	ds_read_b128 v[248:251], v226 offset:8192
	s_waitcnt lgkmcnt(3)
	v_mfma_f32_32x32x16_bf16 v[0:15], v[236:239], v[98:101], v[0:15]
	ds_read_b128 v[252:255], v226 offset:12288
	v_cvt_pk_bf16_f32 v98, v114, v115
	v_cvt_pk_bf16_f32 v99, v106, v107
	v_cvt_pk_bf16_f32 v100, v108, v109
	v_cvt_pk_bf16_f32 v101, v110, v111
	s_nop 0
	s_waitcnt lgkmcnt(3)
	v_mfma_f32_32x32x16_bf16 v[48:63], v[240:243], v[98:101], v[48:63]
	ds_read_b128 v[236:239], v214 offset:16384
	s_waitcnt lgkmcnt(3)
	v_mfma_f32_32x32x16_bf16 v[32:47], v[244:247], v[98:101], v[32:47]
	s_waitcnt vmcnt(0)
	s_barrier
	s_add_u32 s98, s34, s60
	s_addc_u32 s99, s35, s59
	s_add_u32 s98, s98, 0x140fc000
	s_addc_u32 s99, s99, 0
	s_add_u32 s100, s34, s62
	s_addc_u32 s101, s35, s61
	s_add_u32 s100, s100, 0x171b0100
	s_addc_u32 s101, s101, 0
	s_cmp_lg_u64 s[24:25], 0
	s_cselect_b32 s4, s100, s98
	s_cselect_b32 s5, s101, s99
	s_mov_b32 m0, s52
	v_mov_b32_e32 v234, s4
	v_mov_b32_e32 v235, s5
	v_lshl_add_u64 v[234:235], v[176:177], 1, v[234:235]
	global_load_lds_dwordx4 v[234:235], off
	s_cmp_lg_u64 s[26:27], 0
	s_cselect_b32 s4, s100, s98
	s_cselect_b32 s5, s101, s99
	s_mov_b32 m0, s53
	v_mov_b32_e32 v234, s4
	v_mov_b32_e32 v235, s5
	v_lshl_add_u64 v[234:235], v[178:179], 1, v[234:235]
	global_load_lds_dwordx4 v[234:235], off
	s_cmp_lg_u64 s[28:29], 0
	s_cselect_b32 s4, s100, s98
	s_cselect_b32 s5, s101, s99
	s_mov_b32 m0, s54
	v_mov_b32_e32 v234, s4
	v_mov_b32_e32 v235, s5
	v_lshl_add_u64 v[234:235], v[180:181], 1, v[234:235]
	global_load_lds_dwordx4 v[234:235], off
	s_cmp_lg_u64 s[30:31], 0
	s_cselect_b32 s4, s100, s98
	s_cselect_b32 s5, s101, s99
	s_mov_b32 m0, s55
	v_mov_b32_e32 v234, s4
	v_mov_b32_e32 v235, s5
	v_lshl_add_u64 v[234:235], v[182:183], 1, v[234:235]
	global_load_lds_dwordx4 v[234:235], off
	s_cmp_lg_u64 s[6:7], 0
	s_cselect_b32 s4, s100, s98
	s_cselect_b32 s5, s101, s99
	s_mov_b32 m0, s56
	v_mov_b32_e32 v234, s4
	v_mov_b32_e32 v235, s5
	v_lshl_add_u64 v[234:235], v[184:185], 1, v[234:235]
	global_load_lds_dwordx4 v[234:235], off
	ds_read_b128 v[240:243], v215 offset:16384
	s_waitcnt lgkmcnt(3)
	v_mfma_f32_32x32x16_bf16 v[16:31], v[248:251], v[98:101], v[16:31]
	ds_read_b128 v[244:247], v216 offset:16384
	s_waitcnt lgkmcnt(3)
	v_mfma_f32_32x32x16_bf16 v[0:15], v[252:255], v[98:101], v[0:15]
	ds_read_b128 v[248:251], v217 offset:16384
	v_max_f32_e32 v98, v80, v80
	v_max_f32_e32 v97, v98, v97
	v_max3_f32 v97, v97, v82, v83
	v_max3_f32 v97, v97, v84, v85
	v_max3_f32 v97, v97, v86, v87
	v_max3_f32 v97, v97, v88, v89
	v_max3_f32 v97, v97, v90, v91
	v_max3_f32 v97, v97, v92, v93
	v_max3_f32 v97, v97, v94, v95
	ds_bpermute_b32 v98, v229, v97
	s_waitcnt lgkmcnt(0)
	v_max_f32_e32 v96, v98, v98
	v_max_f32_e32 v96, v97, v96
	v_cmp_lt_f32_e32 vcc, 0, v96
	s_cbranch_vccz .LBB0_861_ld
	v_max_f32_e32 v96, v96, v96
	v_max_f32_e32 v96, 0, v96
	v_exp_f32_e64 v98, -v96
	v_pk_add_f32 v[80:81], v[80:81], v[96:97] op_sel_hi:[1,0] neg_lo:[0,1] neg_hi:[0,1]
	v_pk_add_f32 v[82:83], v[82:83], v[96:97] op_sel_hi:[1,0] neg_lo:[0,1] neg_hi:[0,1]
	v_pk_add_f32 v[84:85], v[84:85], v[96:97] op_sel_hi:[1,0] neg_lo:[0,1] neg_hi:[0,1]
	v_mul_f32_e32 v112, v112, v98
	v_pk_add_f32 v[86:87], v[86:87], v[96:97] op_sel_hi:[1,0] neg_lo:[0,1] neg_hi:[0,1]
	v_pk_add_f32 v[88:89], v[88:89], v[96:97] op_sel_hi:[1,0] neg_lo:[0,1] neg_hi:[0,1]
	v_pk_add_f32 v[90:91], v[90:91], v[96:97] op_sel_hi:[1,0] neg_lo:[0,1] neg_hi:[0,1]
	v_pk_add_f32 v[92:93], v[92:93], v[96:97] op_sel_hi:[1,0] neg_lo:[0,1] neg_hi:[0,1]
	v_sub_f32_e32 v79, v79, v96
	v_sub_f32_e32 v78, v78, v96
	v_sub_f32_e32 v77, v77, v96
	v_sub_f32_e32 v76, v76, v96
	v_sub_f32_e32 v75, v75, v96
	v_sub_f32_e32 v74, v74, v96
	v_sub_f32_e32 v73, v73, v96
	v_sub_f32_e32 v72, v72, v96
	v_sub_f32_e32 v71, v71, v96
	v_sub_f32_e32 v70, v70, v96
	v_sub_f32_e32 v69, v69, v96
	v_sub_f32_e32 v68, v68, v96
	v_sub_f32_e32 v67, v67, v96
	v_sub_f32_e32 v66, v66, v96
	v_sub_f32_e32 v65, v65, v96
	v_sub_f32_e32 v64, v64, v96
	v_pk_add_f32 v[94:95], v[94:95], v[96:97] op_sel_hi:[1,0] neg_lo:[0,1] neg_hi:[0,1]
	v_pk_mul_f32 v[62:63], v[62:63], v[98:99] op_sel_hi:[1,0]
	v_pk_mul_f32 v[60:61], v[60:61], v[98:99] op_sel_hi:[1,0]
	v_pk_mul_f32 v[58:59], v[58:59], v[98:99] op_sel_hi:[1,0]
	v_pk_mul_f32 v[56:57], v[56:57], v[98:99] op_sel_hi:[1,0]
	v_pk_mul_f32 v[54:55], v[54:55], v[98:99] op_sel_hi:[1,0]
	v_pk_mul_f32 v[52:53], v[52:53], v[98:99] op_sel_hi:[1,0]
	v_pk_mul_f32 v[50:51], v[50:51], v[98:99] op_sel_hi:[1,0]
	v_pk_mul_f32 v[48:49], v[48:49], v[98:99] op_sel_hi:[1,0]
	v_pk_mul_f32 v[46:47], v[46:47], v[98:99] op_sel_hi:[1,0]
	v_pk_mul_f32 v[44:45], v[44:45], v[98:99] op_sel_hi:[1,0]
	v_pk_mul_f32 v[42:43], v[42:43], v[98:99] op_sel_hi:[1,0]
	v_pk_mul_f32 v[40:41], v[40:41], v[98:99] op_sel_hi:[1,0]
	v_pk_mul_f32 v[38:39], v[38:39], v[98:99] op_sel_hi:[1,0]
	v_pk_mul_f32 v[36:37], v[36:37], v[98:99] op_sel_hi:[1,0]
	v_pk_mul_f32 v[34:35], v[34:35], v[98:99] op_sel_hi:[1,0]
	v_pk_mul_f32 v[32:33], v[32:33], v[98:99] op_sel_hi:[1,0]
	v_pk_mul_f32 v[30:31], v[30:31], v[98:99] op_sel_hi:[1,0]
	v_pk_mul_f32 v[28:29], v[28:29], v[98:99] op_sel_hi:[1,0]
	v_pk_mul_f32 v[26:27], v[26:27], v[98:99] op_sel_hi:[1,0]
	v_pk_mul_f32 v[24:25], v[24:25], v[98:99] op_sel_hi:[1,0]
	v_pk_mul_f32 v[22:23], v[22:23], v[98:99] op_sel_hi:[1,0]
	v_pk_mul_f32 v[20:21], v[20:21], v[98:99] op_sel_hi:[1,0]
	v_pk_mul_f32 v[18:19], v[18:19], v[98:99] op_sel_hi:[1,0]
	v_pk_mul_f32 v[16:17], v[16:17], v[98:99] op_sel_hi:[1,0]
	v_pk_mul_f32 v[14:15], v[14:15], v[98:99] op_sel_hi:[1,0]
	v_pk_mul_f32 v[12:13], v[12:13], v[98:99] op_sel_hi:[1,0]
	v_pk_mul_f32 v[10:11], v[10:11], v[98:99] op_sel_hi:[1,0]
	v_pk_mul_f32 v[8:9], v[8:9], v[98:99] op_sel_hi:[1,0]
	v_pk_mul_f32 v[6:7], v[6:7], v[98:99] op_sel_hi:[1,0]
	v_pk_mul_f32 v[4:5], v[4:5], v[98:99] op_sel_hi:[1,0]
	v_pk_mul_f32 v[2:3], v[2:3], v[98:99] op_sel_hi:[1,0]
	v_pk_mul_f32 v[0:1], v[0:1], v[98:99] op_sel_hi:[1,0]
.LBB0_861_ld:
	v_exp_f32_e32 v113, v80
	v_exp_f32_e32 v122, v81
	v_exp_f32_e32 v123, v82
	v_mfma_f32_32x32x16_bf16 v[96:111], v[236:239], v[144:147], v[64:79]
	ds_read_b128 v[252:255], v218 offset:16384
	v_exp_f32_e32 v124, v83
	v_exp_f32_e32 v125, v84
	v_exp_f32_e32 v126, v85
	v_exp_f32_e32 v127, v86
	v_exp_f32_e32 v230, v87
	v_exp_f32_e32 v88, v88
	v_exp_f32_e32 v89, v89
	v_mfma_f32_32x32x16_bf16 v[96:111], v[240:243], v[156:159], v[96:111]
	ds_read_b128 v[236:239], v219 offset:16384
	v_exp_f32_e32 v90, v90
	v_exp_f32_e32 v91, v91
	v_exp_f32_e32 v92, v92
	v_exp_f32_e32 v93, v93
	v_exp_f32_e32 v94, v94
	v_exp_f32_e32 v95, v95
	v_mfma_f32_32x32x16_bf16 v[96:111], v[244:247], v[168:171], v[96:111]
	ds_read_b128 v[240:243], v220 offset:16384
	v_mfma_f32_32x32x16_bf16 v[96:111], v[248:251], v[172:175], v[96:111]
	ds_read_b128 v[244:247], v221 offset:16384
	s_waitcnt lgkmcnt(3)
	v_mfma_f32_32x32x16_bf16 v[96:111], v[252:255], v[164:167], v[96:111]
	ds_read_b128 v[248:251], v205 offset:57344
	s_waitcnt lgkmcnt(3)
	v_mfma_f32_32x32x16_bf16 v[96:111], v[236:239], v[160:163], v[96:111]
	ds_read_b128 v[252:255], v207 offset:57344
	s_waitcnt lgkmcnt(3)
	v_mfma_f32_32x32x16_bf16 v[96:111], v[240:243], v[152:155], v[96:111]
	ds_read_b128 v[236:239], v209 offset:57344
	s_waitcnt lgkmcnt(3)
	v_mfma_f32_32x32x16_bf16 v[96:111], v[244:247], v[148:151], v[96:111]
	ds_read_b128 v[240:243], v211 offset:57344
	s_waitcnt lgkmcnt(3)
	v_mfma_f32_32x32x16_bf16 v[96:111], v[248:251], v[140:143], v[96:111]
	ds_read_b128 v[244:247], v227
	s_waitcnt lgkmcnt(3)
	v_mfma_f32_32x32x16_bf16 v[96:111], v[252:255], v[136:139], v[96:111]
	ds_read_b128 v[248:251], v227 offset:4096
	s_waitcnt lgkmcnt(3)
	v_mfma_f32_32x32x16_bf16 v[96:111], v[236:239], v[132:135], v[96:111]
	ds_read_b128 v[252:255], v227 offset:8192
	v_cvt_pk_bf16_f32 v114, v113, v122
	v_cvt_pk_bf16_f32 v115, v123, v124
	v_cvt_pk_bf16_f32 v116, v125, v126
	v_cvt_pk_bf16_f32 v117, v127, v230
	s_waitcnt lgkmcnt(3)
	v_mfma_f32_32x32x16_bf16 v[96:111], v[240:243], v[128:131], v[96:111]
	ds_read_b128 v[236:239], v227 offset:12288
	v_add_f32_e32 v118, 0, v113
	v_add_f32_e32 v113, v122, v118
	v_add_f32_e32 v113, v123, v113
	s_waitcnt lgkmcnt(3)
	v_mfma_f32_32x32x16_bf16 v[48:63], v[244:247], v[114:117], v[48:63]
	ds_read_b128 v[240:243], v228 offset:4096
	v_add_f32_e32 v80, v124, v113
	v_add_f32_e32 v80, v125, v80
	v_add_f32_e32 v80, v126, v80
	v_add_f32_e32 v113, v127, v80
	s_waitcnt lgkmcnt(3)
	v_mfma_f32_32x32x16_bf16 v[32:47], v[248:251], v[114:117], v[32:47]
	ds_read_b128 v[244:247], v228
	v_add_f32_e32 v84, v230, v113
	v_add_f32_e32 v84, v88, v84
	v_add_f32_e32 v113, v89, v84
	s_waitcnt lgkmcnt(3)
	v_mfma_f32_32x32x16_bf16 v[16:31], v[252:255], v[114:117], v[16:31]
	ds_read_b128 v[248:251], v228 offset:8192
	v_add_f32_e32 v80, v90, v113
	v_add_f32_e32 v80, v91, v80
	v_add_f32_e32 v80, v92, v80
	v_add_f32_e32 v113, v93, v80
	v_add_f32_e32 v113, v94, v113
	s_waitcnt lgkmcnt(3)
	v_mfma_f32_32x32x16_bf16 v[0:15], v[236:239], v[114:117], v[0:15]
	ds_read_b128 v[252:255], v228 offset:12288
	v_cvt_pk_bf16_f32 v84, v88, v89
	v_cvt_pk_bf16_f32 v85, v90, v91
	v_cvt_pk_bf16_f32 v86, v92, v93
	v_max_f32_e32 v92, v97, v97
	v_max_f32_e32 v93, v96, v96
	v_max_f32_e32 v92, v93, v92
	v_max3_f32 v92, v92, v98, v99
	v_max3_f32 v92, v92, v100, v101
	v_cvt_pk_bf16_f32 v87, v94, v95
	v_max3_f32 v92, v92, v102, v103
	v_add_f32_e32 v94, v95, v113
	s_waitcnt lgkmcnt(3)
	v_mfma_f32_32x32x16_bf16 v[32:47], v[240:243], v[84:87], v[32:47]
	ds_read_b128 v[236:239], v214 offset:24576
	v_max3_f32 v88, v92, v104, v105
	v_max3_f32 v88, v88, v106, v107
	v_max3_f32 v88, v88, v108, v109
	v_max3_f32 v92, v88, v110, v111
	ds_bpermute_b32 v93, v229, v92
	v_add_f32_e32 v112, v112, v94
	s_waitcnt lgkmcnt(4)
	v_mfma_f32_32x32x16_bf16 v[48:63], v[244:247], v[84:87], v[48:63]
	ds_read_b128 v[240:243], v215 offset:24576
	s_waitcnt lgkmcnt(4)
	v_mfma_f32_32x32x16_bf16 v[16:31], v[248:251], v[84:87], v[16:31]
	ds_read_b128 v[244:247], v216 offset:24576
	s_waitcnt lgkmcnt(2)
	v_max_f32_e32 v80, v93, v93
	v_max_f32_e32 v80, v92, v80
	v_cmp_lt_f32_e32 vcc, 0, v80
	v_mfma_f32_32x32x16_bf16 v[0:15], v[252:255], v[84:87], v[0:15]
	ds_read_b128 v[248:251], v217 offset:24576
	s_cbranch_vccz .LBB0_863_ld
	v_max_f32_e32 v80, v80, v80
	v_max_f32_e32 v80, 0, v80
	v_exp_f32_e64 v82, -v80
	v_pk_add_f32 v[96:97], v[96:97], v[80:81] op_sel_hi:[1,0] neg_lo:[0,1] neg_hi:[0,1]
	v_pk_add_f32 v[98:99], v[98:99], v[80:81] op_sel_hi:[1,0] neg_lo:[0,1] neg_hi:[0,1]
	v_pk_add_f32 v[100:101], v[100:101], v[80:81] op_sel_hi:[1,0] neg_lo:[0,1] neg_hi:[0,1]
	v_mul_f32_e32 v112, v112, v82
	v_pk_add_f32 v[102:103], v[102:103], v[80:81] op_sel_hi:[1,0] neg_lo:[0,1] neg_hi:[0,1]
	v_pk_add_f32 v[104:105], v[104:105], v[80:81] op_sel_hi:[1,0] neg_lo:[0,1] neg_hi:[0,1]
	v_pk_add_f32 v[106:107], v[106:107], v[80:81] op_sel_hi:[1,0] neg_lo:[0,1] neg_hi:[0,1]
	v_pk_add_f32 v[108:109], v[108:109], v[80:81] op_sel_hi:[1,0] neg_lo:[0,1] neg_hi:[0,1]
	v_sub_f32_e32 v79, v79, v80
	v_sub_f32_e32 v78, v78, v80
	v_sub_f32_e32 v77, v77, v80
	v_sub_f32_e32 v76, v76, v80
	v_sub_f32_e32 v75, v75, v80
	v_sub_f32_e32 v74, v74, v80
	v_sub_f32_e32 v73, v73, v80
	v_sub_f32_e32 v72, v72, v80
	v_sub_f32_e32 v71, v71, v80
	v_sub_f32_e32 v70, v70, v80
	v_sub_f32_e32 v69, v69, v80
	v_sub_f32_e32 v68, v68, v80
	v_sub_f32_e32 v67, v67, v80
	v_sub_f32_e32 v66, v66, v80
	v_sub_f32_e32 v65, v65, v80
	v_sub_f32_e32 v64, v64, v80
	v_pk_add_f32 v[110:111], v[110:111], v[80:81] op_sel_hi:[1,0] neg_lo:[0,1] neg_hi:[0,1]
	v_pk_mul_f32 v[62:63], v[62:63], v[82:83] op_sel_hi:[1,0]
	v_pk_mul_f32 v[60:61], v[60:61], v[82:83] op_sel_hi:[1,0]
	v_pk_mul_f32 v[58:59], v[58:59], v[82:83] op_sel_hi:[1,0]
	v_pk_mul_f32 v[56:57], v[56:57], v[82:83] op_sel_hi:[1,0]
	v_pk_mul_f32 v[54:55], v[54:55], v[82:83] op_sel_hi:[1,0]
	v_pk_mul_f32 v[52:53], v[52:53], v[82:83] op_sel_hi:[1,0]
	v_pk_mul_f32 v[50:51], v[50:51], v[82:83] op_sel_hi:[1,0]
	v_pk_mul_f32 v[48:49], v[48:49], v[82:83] op_sel_hi:[1,0]
	v_pk_mul_f32 v[46:47], v[46:47], v[82:83] op_sel_hi:[1,0]
	v_pk_mul_f32 v[44:45], v[44:45], v[82:83] op_sel_hi:[1,0]
	v_pk_mul_f32 v[42:43], v[42:43], v[82:83] op_sel_hi:[1,0]
	v_pk_mul_f32 v[40:41], v[40:41], v[82:83] op_sel_hi:[1,0]
	v_pk_mul_f32 v[38:39], v[38:39], v[82:83] op_sel_hi:[1,0]
	v_pk_mul_f32 v[36:37], v[36:37], v[82:83] op_sel_hi:[1,0]
	v_pk_mul_f32 v[34:35], v[34:35], v[82:83] op_sel_hi:[1,0]
	v_pk_mul_f32 v[32:33], v[32:33], v[82:83] op_sel_hi:[1,0]
	v_pk_mul_f32 v[30:31], v[30:31], v[82:83] op_sel_hi:[1,0]
	v_pk_mul_f32 v[28:29], v[28:29], v[82:83] op_sel_hi:[1,0]
	v_pk_mul_f32 v[26:27], v[26:27], v[82:83] op_sel_hi:[1,0]
	v_pk_mul_f32 v[24:25], v[24:25], v[82:83] op_sel_hi:[1,0]
	v_pk_mul_f32 v[22:23], v[22:23], v[82:83] op_sel_hi:[1,0]
	v_pk_mul_f32 v[20:21], v[20:21], v[82:83] op_sel_hi:[1,0]
	v_pk_mul_f32 v[18:19], v[18:19], v[82:83] op_sel_hi:[1,0]
	v_pk_mul_f32 v[16:17], v[16:17], v[82:83] op_sel_hi:[1,0]
	v_pk_mul_f32 v[14:15], v[14:15], v[82:83] op_sel_hi:[1,0]
	v_pk_mul_f32 v[12:13], v[12:13], v[82:83] op_sel_hi:[1,0]
	v_pk_mul_f32 v[10:11], v[10:11], v[82:83] op_sel_hi:[1,0]
	v_pk_mul_f32 v[8:9], v[8:9], v[82:83] op_sel_hi:[1,0]
	v_pk_mul_f32 v[6:7], v[6:7], v[82:83] op_sel_hi:[1,0]
	v_pk_mul_f32 v[4:5], v[4:5], v[82:83] op_sel_hi:[1,0]
	v_pk_mul_f32 v[2:3], v[2:3], v[82:83] op_sel_hi:[1,0]
	v_pk_mul_f32 v[0:1], v[0:1], v[82:83] op_sel_hi:[1,0]
.LBB0_863_ld:
	v_exp_f32_e32 v96, v96
	v_exp_f32_e32 v97, v97
	v_exp_f32_e32 v98, v98
	v_mfma_f32_32x32x16_bf16 v[80:95], v[236:239], v[144:147], v[64:79]
	ds_read_b128 v[252:255], v218 offset:24576
	v_exp_f32_e32 v99, v99
	v_exp_f32_e32 v100, v100
	v_exp_f32_e32 v101, v101
	v_exp_f32_e32 v102, v102
	v_exp_f32_e32 v103, v103
	v_cvt_pk_bf16_f32 v122, v96, v97
	v_cvt_pk_bf16_f32 v123, v98, v99
	s_waitcnt lgkmcnt(3)
	v_mfma_f32_32x32x16_bf16 v[80:95], v[240:243], v[156:159], v[80:95]
	ds_read_b128 v[236:239], v219 offset:24576
	v_cvt_pk_bf16_f32 v124, v100, v101
	v_cvt_pk_bf16_f32 v125, v102, v103
	v_exp_f32_e32 v104, v104
	v_exp_f32_e32 v105, v105
	v_exp_f32_e32 v106, v106
	v_exp_f32_e32 v107, v107
	s_waitcnt lgkmcnt(3)
	v_mfma_f32_32x32x16_bf16 v[80:95], v[244:247], v[168:171], v[80:95]
	ds_read_b128 v[240:243], v220 offset:24576
	v_exp_f32_e32 v108, v108
	v_exp_f32_e32 v109, v109
	v_exp_f32_e32 v110, v110
	v_exp_f32_e32 v111, v111
	s_add_i32 s16, s8, 3
	s_cmp_lt_u32 s16, s9
	s_cselect_b64 s[10:11], -1, 0
	s_waitcnt lgkmcnt(3)
	v_mfma_f32_32x32x16_bf16 v[80:95], v[248:251], v[172:175], v[80:95]
	ds_read_b128 v[244:247], v221 offset:24576
	s_cmp_ge_u32 s16, s9
	s_waitcnt lgkmcnt(3)
	v_mfma_f32_32x32x16_bf16 v[80:95], v[252:255], v[164:167], v[80:95]
	ds_read_b128 v[248:251], v205 offset:61440
	s_waitcnt lgkmcnt(3)
	v_mfma_f32_32x32x16_bf16 v[80:95], v[236:239], v[160:163], v[80:95]
	ds_read_b128 v[252:255], v207 offset:61440
	s_waitcnt lgkmcnt(3)
	v_mfma_f32_32x32x16_bf16 v[80:95], v[240:243], v[152:155], v[80:95]
	ds_read_b128 v[236:239], v209 offset:61440
	s_waitcnt lgkmcnt(3)
	v_mfma_f32_32x32x16_bf16 v[80:95], v[244:247], v[148:151], v[80:95]
	ds_read_b128 v[240:243], v211 offset:61440
	s_waitcnt lgkmcnt(3)
	v_mfma_f32_32x32x16_bf16 v[80:95], v[248:251], v[140:143], v[80:95]
	ds_read_b128 v[244:247], v225 offset:16384
	s_waitcnt lgkmcnt(3)
	v_mfma_f32_32x32x16_bf16 v[80:95], v[252:255], v[136:139], v[80:95]
	ds_read_b128 v[248:251], v225 offset:20480
	s_waitcnt lgkmcnt(3)
	v_mfma_f32_32x32x16_bf16 v[80:95], v[236:239], v[132:135], v[80:95]
	ds_read_b128 v[252:255], v225 offset:24576
	s_waitcnt lgkmcnt(3)
	v_mfma_f32_32x32x16_bf16 v[80:95], v[240:243], v[128:131], v[80:95]
	ds_read_b128 v[236:239], v225 offset:28672
	s_waitcnt lgkmcnt(3)
	v_mfma_f32_32x32x16_bf16 v[48:63], v[244:247], v[122:125], v[48:63]
	ds_read_b128 v[240:243], v226 offset:16384
	s_nop 8
	v_max_f32_e32 v113, v81, v81
	v_max_f32_e32 v126, v80, v80
	v_max_f32_e32 v113, v126, v113
	v_max3_f32 v113, v113, v82, v83
	v_max3_f32 v113, v113, v84, v85
	v_max3_f32 v113, v113, v86, v87
	v_max3_f32 v113, v113, v88, v89
	s_waitcnt lgkmcnt(3)
	v_mfma_f32_32x32x16_bf16 v[32:47], v[248:251], v[122:125], v[32:47]
	ds_read_b128 v[244:247], v226 offset:20480
	v_max3_f32 v113, v113, v90, v91
	v_max3_f32 v113, v113, v92, v93
	v_max3_f32 v113, v113, v94, v95
	s_waitcnt lgkmcnt(3)
	v_mfma_f32_32x32x16_bf16 v[16:31], v[252:255], v[122:125], v[16:31]
	ds_read_b128 v[248:251], v226 offset:24576
	s_waitcnt lgkmcnt(3)
	v_mfma_f32_32x32x16_bf16 v[0:15], v[236:239], v[122:125], v[0:15]
	ds_read_b128 v[252:255], v226 offset:28672
	v_cvt_pk_bf16_f32 v118, v104, v105
	v_cvt_pk_bf16_f32 v119, v106, v107
	v_cvt_pk_bf16_f32 v120, v108, v109
	v_cvt_pk_bf16_f32 v121, v110, v111
	s_nop 0
	s_waitcnt lgkmcnt(3)
	v_mfma_f32_32x32x16_bf16 v[48:63], v[240:243], v[118:121], v[48:63]
	ds_read_b128 v[236:239], v214 offset:32768
	s_waitcnt lgkmcnt(3)
	v_mfma_f32_32x32x16_bf16 v[32:47], v[244:247], v[118:121], v[32:47]
	s_waitcnt vmcnt(0)
	s_barrier
	s_add_i32 s4, s8, 3
	s_cmp_ge_u32 s4, s9
	s_cbranch_scc1 .Lmla_dma_skip_t1_ld
	s_add_u32 s98, s34, s60
	s_addc_u32 s99, s35, s59
	s_add_u32 s98, s98, 0x14102000
	s_addc_u32 s99, s99, 0
	s_add_u32 s100, s34, s62
	s_addc_u32 s101, s35, s61
	s_add_u32 s100, s100, 0x171b0180
	s_addc_u32 s101, s101, 0
	s_cmp_lg_u64 s[24:25], 0
	s_cselect_b32 s4, s100, s98
	s_cselect_b32 s5, s101, s99
	s_mov_b32 m0, s41
	v_mov_b32_e32 v234, s4
	v_mov_b32_e32 v235, s5
	v_lshl_add_u64 v[234:235], v[176:177], 1, v[234:235]
	global_load_lds_dwordx4 v[234:235], off
	s_cmp_lg_u64 s[26:27], 0
	s_cselect_b32 s4, s100, s98
	s_cselect_b32 s5, s101, s99
	s_mov_b32 m0, s42
	v_mov_b32_e32 v234, s4
	v_mov_b32_e32 v235, s5
	v_lshl_add_u64 v[234:235], v[178:179], 1, v[234:235]
	global_load_lds_dwordx4 v[234:235], off
	s_cmp_lg_u64 s[28:29], 0
	s_cselect_b32 s4, s100, s98
	s_cselect_b32 s5, s101, s99
	s_mov_b32 m0, s43
	v_mov_b32_e32 v234, s4
	v_mov_b32_e32 v235, s5
	v_lshl_add_u64 v[234:235], v[180:181], 1, v[234:235]
	global_load_lds_dwordx4 v[234:235], off
	s_cmp_lg_u64 s[30:31], 0
	s_cselect_b32 s4, s100, s98
	s_cselect_b32 s5, s101, s99
	s_mov_b32 m0, s44
	v_mov_b32_e32 v234, s4
	v_mov_b32_e32 v235, s5
	v_lshl_add_u64 v[234:235], v[182:183], 1, v[234:235]
	global_load_lds_dwordx4 v[234:235], off
	s_cmp_lg_u64 s[6:7], 0
	s_cselect_b32 s4, s100, s98
	s_cselect_b32 s5, s101, s99
	s_mov_b32 m0, s45
	v_mov_b32_e32 v234, s4
	v_mov_b32_e32 v235, s5
	v_lshl_add_u64 v[234:235], v[184:185], 1, v[234:235]
	global_load_lds_dwordx4 v[234:235], off
.Lmla_dma_skip_t1_ld:
	ds_read_b128 v[240:243], v215 offset:32768
	s_waitcnt lgkmcnt(3)
	v_mfma_f32_32x32x16_bf16 v[16:31], v[248:251], v[118:121], v[16:31]
	ds_read_b128 v[244:247], v216 offset:32768
	ds_bpermute_b32 v114, v229, v113
	s_waitcnt lgkmcnt(4)
	v_mfma_f32_32x32x16_bf16 v[0:15], v[252:255], v[118:121], v[0:15]
	ds_read_b128 v[248:251], v217 offset:32768

.LBB0_867_ld:
	v_exp_f32_e32 v113, v80
	v_exp_f32_e32 v122, v81
	v_exp_f32_e32 v123, v82
	v_mfma_f32_32x32x16_bf16 v[96:111], v[236:239], v[144:147], v[64:79]
	ds_read_b128 v[252:255], v218 offset:32768
	v_exp_f32_e32 v124, v83
	v_exp_f32_e32 v125, v84
	v_exp_f32_e32 v126, v85
	v_exp_f32_e32 v127, v86
	v_exp_f32_e32 v230, v87
	v_exp_f32_e32 v88, v88
	v_exp_f32_e32 v89, v89
	v_mfma_f32_32x32x16_bf16 v[96:111], v[240:243], v[156:159], v[96:111]
	ds_read_b128 v[236:239], v219 offset:32768
	v_exp_f32_e32 v90, v90
	v_exp_f32_e32 v91, v91
	v_exp_f32_e32 v92, v92
	v_exp_f32_e32 v93, v93
	v_exp_f32_e32 v94, v94
	v_exp_f32_e32 v95, v95
	v_mfma_f32_32x32x16_bf16 v[96:111], v[244:247], v[168:171], v[96:111]
	ds_read_b128 v[240:243], v220 offset:32768
	s_waitcnt lgkmcnt(3)
	v_mfma_f32_32x32x16_bf16 v[96:111], v[248:251], v[172:175], v[96:111]
	ds_read_b128 v[244:247], v221 offset:32768
	s_waitcnt lgkmcnt(3)
	v_mfma_f32_32x32x16_bf16 v[96:111], v[252:255], v[164:167], v[96:111]
	ds_read_b128 v[248:251], v206 offset:16384
	s_waitcnt lgkmcnt(3)
	v_mfma_f32_32x32x16_bf16 v[96:111], v[236:239], v[160:163], v[96:111]
	ds_read_b128 v[252:255], v208 offset:16384
	s_waitcnt lgkmcnt(3)
	v_mfma_f32_32x32x16_bf16 v[96:111], v[240:243], v[152:155], v[96:111]
	ds_read_b128 v[236:239], v210 offset:16384
	s_waitcnt lgkmcnt(3)
	v_mfma_f32_32x32x16_bf16 v[96:111], v[244:247], v[148:151], v[96:111]
	ds_read_b128 v[240:243], v212 offset:16384
	s_waitcnt lgkmcnt(3)
	v_mfma_f32_32x32x16_bf16 v[96:111], v[248:251], v[140:143], v[96:111]
	ds_read_b128 v[244:247], v227 offset:16384
	s_waitcnt lgkmcnt(3)
	v_mfma_f32_32x32x16_bf16 v[96:111], v[252:255], v[136:139], v[96:111]
	ds_read_b128 v[248:251], v227 offset:20480
	s_waitcnt lgkmcnt(3)
	v_mfma_f32_32x32x16_bf16 v[96:111], v[236:239], v[132:135], v[96:111]
	ds_read_b128 v[252:255], v227 offset:24576
	v_cvt_pk_bf16_f32 v114, v113, v122
	v_cvt_pk_bf16_f32 v115, v123, v124
	v_cvt_pk_bf16_f32 v116, v125, v126
	v_cvt_pk_bf16_f32 v117, v127, v230
	s_waitcnt lgkmcnt(3)
	v_mfma_f32_32x32x16_bf16 v[96:111], v[240:243], v[128:131], v[96:111]
	ds_read_b128 v[236:239], v227 offset:28672
	v_add_f32_e32 v118, 0, v113
	v_add_f32_e32 v113, v122, v118
	v_add_f32_e32 v113, v123, v113
	s_waitcnt lgkmcnt(3)
	v_mfma_f32_32x32x16_bf16 v[48:63], v[244:247], v[114:117], v[48:63]
	ds_read_b128 v[240:243], v228 offset:20480
	v_add_f32_e32 v80, v124, v113
	v_add_f32_e32 v80, v125, v80
	v_add_f32_e32 v80, v126, v80
	v_add_f32_e32 v113, v127, v80
	s_waitcnt lgkmcnt(3)
	v_mfma_f32_32x32x16_bf16 v[32:47], v[248:251], v[114:117], v[32:47]
	ds_read_b128 v[244:247], v228 offset:16384
	v_add_f32_e32 v84, v230, v113
	v_add_f32_e32 v84, v88, v84
	v_add_f32_e32 v113, v89, v84
	s_waitcnt lgkmcnt(3)
	v_mfma_f32_32x32x16_bf16 v[16:31], v[252:255], v[114:117], v[16:31]
	ds_read_b128 v[248:251], v228 offset:24576
	v_add_f32_e32 v80, v90, v113
	v_add_f32_e32 v80, v91, v80
	v_add_f32_e32 v80, v92, v80
	v_add_f32_e32 v113, v93, v80
	v_add_f32_e32 v113, v94, v113
	s_waitcnt lgkmcnt(3)
	v_mfma_f32_32x32x16_bf16 v[0:15], v[236:239], v[114:117], v[0:15]
	ds_read_b128 v[252:255], v228 offset:28672
	v_cvt_pk_bf16_f32 v84, v88, v89
	v_cvt_pk_bf16_f32 v85, v90, v91
	v_cvt_pk_bf16_f32 v86, v92, v93
	v_max_f32_e32 v92, v97, v97
	v_max_f32_e32 v93, v96, v96
	v_max_f32_e32 v92, v93, v92
	v_max3_f32 v92, v92, v98, v99
	v_max3_f32 v92, v92, v100, v101
	v_cvt_pk_bf16_f32 v87, v94, v95
	v_max3_f32 v92, v92, v102, v103
	v_add_f32_e32 v94, v95, v113
	s_waitcnt lgkmcnt(3)
	v_mfma_f32_32x32x16_bf16 v[32:47], v[240:243], v[84:87], v[32:47]
	ds_read_b128 v[236:239], v214 offset:40960
	v_max3_f32 v88, v92, v104, v105
	v_max3_f32 v88, v88, v106, v107
	v_max3_f32 v88, v88, v108, v109
	v_max3_f32 v92, v88, v110, v111
	ds_bpermute_b32 v93, v229, v92
	v_add_f32_e32 v112, v112, v94
	s_waitcnt lgkmcnt(4)
	v_mfma_f32_32x32x16_bf16 v[48:63], v[244:247], v[84:87], v[48:63]
	ds_read_b128 v[240:243], v215 offset:40960
	s_waitcnt lgkmcnt(4)
	v_mfma_f32_32x32x16_bf16 v[16:31], v[248:251], v[84:87], v[16:31]
	ds_read_b128 v[244:247], v216 offset:40960
	s_waitcnt lgkmcnt(2)
	v_max_f32_e32 v80, v93, v93
	v_max_f32_e32 v80, v92, v80
	v_cmp_lt_f32_e32 vcc, 0, v80
	v_mfma_f32_32x32x16_bf16 v[0:15], v[252:255], v[84:87], v[0:15]
	ds_read_b128 v[248:251], v217 offset:40960
	s_cbranch_vccz .LBB0_869_ld
	v_max_f32_e32 v80, v80, v80
	v_max_f32_e32 v80, 0, v80
	v_exp_f32_e64 v82, -v80
	v_pk_add_f32 v[96:97], v[96:97], v[80:81] op_sel_hi:[1,0] neg_lo:[0,1] neg_hi:[0,1]
	v_pk_add_f32 v[98:99], v[98:99], v[80:81] op_sel_hi:[1,0] neg_lo:[0,1] neg_hi:[0,1]
	v_pk_add_f32 v[100:101], v[100:101], v[80:81] op_sel_hi:[1,0] neg_lo:[0,1] neg_hi:[0,1]
	v_mul_f32_e32 v112, v112, v82
	v_pk_add_f32 v[102:103], v[102:103], v[80:81] op_sel_hi:[1,0] neg_lo:[0,1] neg_hi:[0,1]
	v_pk_add_f32 v[104:105], v[104:105], v[80:81] op_sel_hi:[1,0] neg_lo:[0,1] neg_hi:[0,1]
	v_pk_add_f32 v[106:107], v[106:107], v[80:81] op_sel_hi:[1,0] neg_lo:[0,1] neg_hi:[0,1]
	v_pk_add_f32 v[108:109], v[108:109], v[80:81] op_sel_hi:[1,0] neg_lo:[0,1] neg_hi:[0,1]
	v_sub_f32_e32 v79, v79, v80
	v_sub_f32_e32 v78, v78, v80
	v_sub_f32_e32 v77, v77, v80
	v_sub_f32_e32 v76, v76, v80
	v_sub_f32_e32 v75, v75, v80
	v_sub_f32_e32 v74, v74, v80
	v_sub_f32_e32 v73, v73, v80
	v_sub_f32_e32 v72, v72, v80
	v_sub_f32_e32 v71, v71, v80
	v_sub_f32_e32 v70, v70, v80
	v_sub_f32_e32 v69, v69, v80
	v_sub_f32_e32 v68, v68, v80
	v_sub_f32_e32 v67, v67, v80
	v_sub_f32_e32 v66, v66, v80
	v_sub_f32_e32 v65, v65, v80
	v_sub_f32_e32 v64, v64, v80
	v_pk_add_f32 v[110:111], v[110:111], v[80:81] op_sel_hi:[1,0] neg_lo:[0,1] neg_hi:[0,1]
	v_pk_mul_f32 v[62:63], v[62:63], v[82:83] op_sel_hi:[1,0]
	v_pk_mul_f32 v[60:61], v[60:61], v[82:83] op_sel_hi:[1,0]
	v_pk_mul_f32 v[58:59], v[58:59], v[82:83] op_sel_hi:[1,0]
	v_pk_mul_f32 v[56:57], v[56:57], v[82:83] op_sel_hi:[1,0]
	v_pk_mul_f32 v[54:55], v[54:55], v[82:83] op_sel_hi:[1,0]
	v_pk_mul_f32 v[52:53], v[52:53], v[82:83] op_sel_hi:[1,0]
	v_pk_mul_f32 v[50:51], v[50:51], v[82:83] op_sel_hi:[1,0]
	v_pk_mul_f32 v[48:49], v[48:49], v[82:83] op_sel_hi:[1,0]
	v_pk_mul_f32 v[46:47], v[46:47], v[82:83] op_sel_hi:[1,0]
	v_pk_mul_f32 v[44:45], v[44:45], v[82:83] op_sel_hi:[1,0]
	v_pk_mul_f32 v[42:43], v[42:43], v[82:83] op_sel_hi:[1,0]
	v_pk_mul_f32 v[40:41], v[40:41], v[82:83] op_sel_hi:[1,0]
	v_pk_mul_f32 v[38:39], v[38:39], v[82:83] op_sel_hi:[1,0]
	v_pk_mul_f32 v[36:37], v[36:37], v[82:83] op_sel_hi:[1,0]
	v_pk_mul_f32 v[34:35], v[34:35], v[82:83] op_sel_hi:[1,0]
	v_pk_mul_f32 v[32:33], v[32:33], v[82:83] op_sel_hi:[1,0]
	v_pk_mul_f32 v[30:31], v[30:31], v[82:83] op_sel_hi:[1,0]
	v_pk_mul_f32 v[28:29], v[28:29], v[82:83] op_sel_hi:[1,0]
	v_pk_mul_f32 v[26:27], v[26:27], v[82:83] op_sel_hi:[1,0]
	v_pk_mul_f32 v[24:25], v[24:25], v[82:83] op_sel_hi:[1,0]
	v_pk_mul_f32 v[22:23], v[22:23], v[82:83] op_sel_hi:[1,0]
	v_pk_mul_f32 v[20:21], v[20:21], v[82:83] op_sel_hi:[1,0]
	v_pk_mul_f32 v[18:19], v[18:19], v[82:83] op_sel_hi:[1,0]
	v_pk_mul_f32 v[16:17], v[16:17], v[82:83] op_sel_hi:[1,0]
	v_pk_mul_f32 v[14:15], v[14:15], v[82:83] op_sel_hi:[1,0]
	v_pk_mul_f32 v[12:13], v[12:13], v[82:83] op_sel_hi:[1,0]
	v_pk_mul_f32 v[10:11], v[10:11], v[82:83] op_sel_hi:[1,0]
	v_pk_mul_f32 v[8:9], v[8:9], v[82:83] op_sel_hi:[1,0]
	v_pk_mul_f32 v[6:7], v[6:7], v[82:83] op_sel_hi:[1,0]
	v_pk_mul_f32 v[4:5], v[4:5], v[82:83] op_sel_hi:[1,0]
	v_pk_mul_f32 v[2:3], v[2:3], v[82:83] op_sel_hi:[1,0]
	v_pk_mul_f32 v[0:1], v[0:1], v[82:83] op_sel_hi:[1,0]
.LBB0_869_ld:
	v_exp_f32_e32 v96, v96
	v_exp_f32_e32 v97, v97
	v_exp_f32_e32 v98, v98
	v_mfma_f32_32x32x16_bf16 v[80:95], v[236:239], v[144:147], v[64:79]
	ds_read_b128 v[252:255], v218 offset:40960
	v_exp_f32_e32 v99, v99
	v_exp_f32_e32 v100, v100
	v_exp_f32_e32 v101, v101
	v_exp_f32_e32 v102, v102
	v_exp_f32_e32 v103, v103
	v_cvt_pk_bf16_f32 v122, v96, v97
	v_cvt_pk_bf16_f32 v123, v98, v99
	s_waitcnt lgkmcnt(3)
	v_mfma_f32_32x32x16_bf16 v[80:95], v[240:243], v[156:159], v[80:95]
	ds_read_b128 v[236:239], v219 offset:40960
	v_cvt_pk_bf16_f32 v124, v100, v101
	v_cvt_pk_bf16_f32 v125, v102, v103
	v_exp_f32_e32 v104, v104
	v_exp_f32_e32 v105, v105
	v_exp_f32_e32 v106, v106
	v_exp_f32_e32 v107, v107
	s_waitcnt lgkmcnt(3)
	v_mfma_f32_32x32x16_bf16 v[80:95], v[244:247], v[168:171], v[80:95]
	ds_read_b128 v[240:243], v220 offset:40960
	v_exp_f32_e32 v108, v108
	v_exp_f32_e32 v109, v109
	v_exp_f32_e32 v110, v110
	v_exp_f32_e32 v111, v111
	s_add_i32 s4, s8, 4
	s_cmp_ge_u32 s4, s9
	s_waitcnt lgkmcnt(3)
	v_mfma_f32_32x32x16_bf16 v[80:95], v[248:251], v[172:175], v[80:95]
	ds_read_b128 v[244:247], v221 offset:40960
	s_waitcnt lgkmcnt(3)
	v_mfma_f32_32x32x16_bf16 v[80:95], v[252:255], v[164:167], v[80:95]
	ds_read_b128 v[248:251], v206 offset:20480
	s_waitcnt lgkmcnt(3)
	v_mfma_f32_32x32x16_bf16 v[80:95], v[236:239], v[160:163], v[80:95]
	ds_read_b128 v[252:255], v208 offset:20480
	s_waitcnt lgkmcnt(3)
	v_mfma_f32_32x32x16_bf16 v[80:95], v[240:243], v[152:155], v[80:95]
	ds_read_b128 v[236:239], v210 offset:20480
	s_waitcnt lgkmcnt(3)
	v_mfma_f32_32x32x16_bf16 v[80:95], v[244:247], v[148:151], v[80:95]
	ds_read_b128 v[240:243], v212 offset:20480
	s_waitcnt lgkmcnt(3)
	v_mfma_f32_32x32x16_bf16 v[80:95], v[248:251], v[140:143], v[80:95]
	ds_read_b128 v[244:247], v225 offset:32768
	s_waitcnt lgkmcnt(3)
	v_mfma_f32_32x32x16_bf16 v[80:95], v[252:255], v[136:139], v[80:95]
	ds_read_b128 v[248:251], v225 offset:36864
	s_waitcnt lgkmcnt(3)
	v_mfma_f32_32x32x16_bf16 v[80:95], v[236:239], v[132:135], v[80:95]
	ds_read_b128 v[252:255], v225 offset:40960
	s_waitcnt lgkmcnt(3)
	v_mfma_f32_32x32x16_bf16 v[80:95], v[240:243], v[128:131], v[80:95]
	ds_read_b128 v[236:239], v225 offset:45056
	s_waitcnt lgkmcnt(3)
	v_mfma_f32_32x32x16_bf16 v[48:63], v[244:247], v[122:125], v[48:63]
	ds_read_b128 v[240:243], v226 offset:32768
	s_nop 8
	v_max_f32_e32 v113, v81, v81
	v_max_f32_e32 v126, v80, v80
	v_max_f32_e32 v113, v126, v113
	v_max3_f32 v113, v113, v82, v83
	v_max3_f32 v113, v113, v84, v85
	v_max3_f32 v113, v113, v86, v87
	v_max3_f32 v113, v113, v88, v89
	s_waitcnt lgkmcnt(3)
	v_mfma_f32_32x32x16_bf16 v[32:47], v[248:251], v[122:125], v[32:47]
	ds_read_b128 v[244:247], v226 offset:36864
	v_max3_f32 v113, v113, v90, v91
	v_max3_f32 v113, v113, v92, v93
	v_max3_f32 v113, v113, v94, v95
	s_waitcnt lgkmcnt(3)
	v_mfma_f32_32x32x16_bf16 v[16:31], v[252:255], v[122:125], v[16:31]
	ds_read_b128 v[248:251], v226 offset:40960
	s_waitcnt lgkmcnt(3)
	v_mfma_f32_32x32x16_bf16 v[0:15], v[236:239], v[122:125], v[0:15]
	ds_read_b128 v[252:255], v226 offset:45056
	v_cvt_pk_bf16_f32 v118, v104, v105
	v_cvt_pk_bf16_f32 v119, v106, v107
	v_cvt_pk_bf16_f32 v120, v108, v109
	v_cvt_pk_bf16_f32 v121, v110, v111
	s_nop 0
	s_waitcnt lgkmcnt(3)
	v_mfma_f32_32x32x16_bf16 v[48:63], v[240:243], v[118:121], v[48:63]
	ds_read_b128 v[236:239], v214
	s_waitcnt lgkmcnt(3)
	v_mfma_f32_32x32x16_bf16 v[32:47], v[244:247], v[118:121], v[32:47]
	s_waitcnt vmcnt(0)
	s_barrier
	s_add_i32 s4, s8, 4
	s_cmp_ge_u32 s4, s9
	s_cbranch_scc1 .Lmla_dma_skip_t2_ld
	s_add_u32 s98, s34, s60
	s_addc_u32 s99, s35, s59
	s_add_u32 s98, s98, 0x14108000
	s_addc_u32 s99, s99, 0
	s_add_u32 s100, s34, s62
	s_addc_u32 s101, s35, s61
	s_add_u32 s100, s100, 0x171b0200
	s_addc_u32 s101, s101, 0
	s_cmp_lg_u64 s[24:25], 0
	s_cselect_b32 s4, s100, s98
	s_cselect_b32 s5, s101, s99
	s_mov_b32 m0, s46
	v_mov_b32_e32 v234, s4
	v_mov_b32_e32 v235, s5
	v_lshl_add_u64 v[234:235], v[176:177], 1, v[234:235]
	global_load_lds_dwordx4 v[234:235], off
	s_cmp_lg_u64 s[26:27], 0
	s_cselect_b32 s4, s100, s98
	s_cselect_b32 s5, s101, s99
	s_mov_b32 m0, s47
	v_mov_b32_e32 v234, s4
	v_mov_b32_e32 v235, s5
	v_lshl_add_u64 v[234:235], v[178:179], 1, v[234:235]
	global_load_lds_dwordx4 v[234:235], off
	s_cmp_lg_u64 s[28:29], 0
	s_cselect_b32 s4, s100, s98
	s_cselect_b32 s5, s101, s99
	s_mov_b32 m0, s48
	v_mov_b32_e32 v234, s4
	v_mov_b32_e32 v235, s5
	v_lshl_add_u64 v[234:235], v[180:181], 1, v[234:235]
	global_load_lds_dwordx4 v[234:235], off
	s_cmp_lg_u64 s[30:31], 0
	s_cselect_b32 s4, s100, s98
	s_cselect_b32 s5, s101, s99
	s_mov_b32 m0, s49
	v_mov_b32_e32 v234, s4
	v_mov_b32_e32 v235, s5
	v_lshl_add_u64 v[234:235], v[182:183], 1, v[234:235]
	global_load_lds_dwordx4 v[234:235], off
	s_cmp_lg_u64 s[6:7], 0
	s_cselect_b32 s4, s100, s98
	s_cselect_b32 s5, s101, s99
	s_mov_b32 m0, s50
	v_mov_b32_e32 v234, s4
	v_mov_b32_e32 v235, s5
	v_lshl_add_u64 v[234:235], v[184:185], 1, v[234:235]
	global_load_lds_dwordx4 v[234:235], off
.Lmla_dma_skip_t2_ld:
	ds_read_b128 v[240:243], v215
	s_waitcnt lgkmcnt(3)
	v_mfma_f32_32x32x16_bf16 v[16:31], v[248:251], v[118:121], v[16:31]
	ds_read_b128 v[244:247], v216
	ds_bpermute_b32 v114, v229, v113
	s_waitcnt lgkmcnt(4)
	v_mfma_f32_32x32x16_bf16 v[0:15], v[252:255], v[118:121], v[0:15]
	ds_read_b128 v[248:251], v217

.LBB0_873_ld:
	v_exp_f32_e32 v113, v80
	v_exp_f32_e32 v126, v85
	v_exp_f32_e32 v127, v86
	v_mfma_f32_32x32x16_bf16 v[96:111], v[236:239], v[144:147], v[64:79]
	ds_read_b128 v[252:255], v218
	v_add_f32_e32 v231, 0, v113
	v_exp_f32_e32 v230, v87
	v_exp_f32_e32 v88, v88
	v_exp_f32_e32 v89, v89
	v_exp_f32_e32 v90, v90
	v_exp_f32_e32 v91, v91
	v_exp_f32_e32 v92, v92
	v_mfma_f32_32x32x16_bf16 v[96:111], v[240:243], v[156:159], v[96:111]
	ds_read_b128 v[236:239], v219
	v_exp_f32_e32 v93, v93
	s_add_u32 s62, s62, 0x180
	s_addc_u32 s61, s61, 0
	s_add_u32 s60, s60, 0x12000
	s_addc_u32 s59, s59, 0
	s_add_i32 s4, s16, 3
	v_mfma_f32_32x32x16_bf16 v[96:111], v[244:247], v[168:171], v[96:111]
	ds_read_b128 v[240:243], v220
	s_cmp_le_u32 s4, s9
	s_waitcnt lgkmcnt(3)
	v_mfma_f32_32x32x16_bf16 v[96:111], v[248:251], v[172:175], v[96:111]
	ds_read_b128 v[244:247], v221
	s_waitcnt lgkmcnt(3)
	v_mfma_f32_32x32x16_bf16 v[96:111], v[252:255], v[164:167], v[96:111]
	ds_read_b128 v[248:251], v206
	s_waitcnt lgkmcnt(3)
	v_mfma_f32_32x32x16_bf16 v[96:111], v[236:239], v[160:163], v[96:111]
	ds_read_b128 v[252:255], v208
	s_waitcnt lgkmcnt(3)
	v_mfma_f32_32x32x16_bf16 v[96:111], v[240:243], v[152:155], v[96:111]
	ds_read_b128 v[236:239], v210
	s_waitcnt lgkmcnt(3)
	v_mfma_f32_32x32x16_bf16 v[96:111], v[244:247], v[148:151], v[96:111]
	ds_read_b128 v[240:243], v212
	s_waitcnt lgkmcnt(3)
	v_mfma_f32_32x32x16_bf16 v[96:111], v[248:251], v[140:143], v[96:111]
	ds_read_b128 v[244:247], v227 offset:32768
	s_waitcnt lgkmcnt(3)
	v_mfma_f32_32x32x16_bf16 v[96:111], v[252:255], v[136:139], v[96:111]
	ds_read_b128 v[248:251], v227 offset:36864
	v_exp_f32_e32 v118, v81
	v_exp_f32_e32 v119, v82
	v_exp_f32_e32 v120, v83
	v_exp_f32_e32 v121, v84
	s_waitcnt lgkmcnt(3)
	v_mfma_f32_32x32x16_bf16 v[96:111], v[236:239], v[132:135], v[96:111]
	ds_read_b128 v[252:255], v227 offset:40960
	v_cvt_pk_bf16_f32 v114, v113, v118
	v_add_f32_e32 v113, v118, v231
	v_add_f32_e32 v113, v119, v113
	v_add_f32_e32 v113, v120, v113
	v_add_f32_e32 v113, v121, v113
	v_cvt_pk_bf16_f32 v115, v119, v120
	v_cvt_pk_bf16_f32 v116, v121, v126
	v_cvt_pk_bf16_f32 v117, v127, v230
	v_add_f32_e32 v113, v126, v113
	s_waitcnt lgkmcnt(3)
	v_mfma_f32_32x32x16_bf16 v[96:111], v[240:243], v[128:131], v[96:111]
	ds_read_b128 v[236:239], v227 offset:45056
	v_exp_f32_e32 v118, v94
	v_exp_f32_e32 v119, v95
	s_waitcnt lgkmcnt(3)
	v_mfma_f32_32x32x16_bf16 v[48:63], v[244:247], v[114:117], v[48:63]
	ds_read_b128 v[240:243], v228 offset:36864
	v_add_f32_e32 v80, v127, v113
	v_add_f32_e32 v80, v230, v80
	v_add_f32_e32 v113, v88, v80
	v_cvt_pk_bf16_f32 v88, v88, v89
	s_waitcnt lgkmcnt(3)
	v_mfma_f32_32x32x16_bf16 v[32:47], v[248:251], v[114:117], v[32:47]
	ds_read_b128 v[244:247], v228 offset:32768
	v_add_f32_e32 v84, v89, v113
	v_add_f32_e32 v84, v90, v84
	v_add_f32_e32 v84, v91, v84
	v_add_f32_e32 v113, v92, v84
	v_add_f32_e32 v113, v93, v113
	v_cvt_pk_bf16_f32 v89, v90, v91
	s_waitcnt lgkmcnt(3)
	v_mfma_f32_32x32x16_bf16 v[16:31], v[252:255], v[114:117], v[16:31]
	ds_read_b128 v[248:251], v228 offset:40960
	v_cvt_pk_bf16_f32 v90, v92, v93
	v_cvt_pk_bf16_f32 v91, v118, v119
	s_waitcnt lgkmcnt(3)
	v_mfma_f32_32x32x16_bf16 v[0:15], v[236:239], v[114:117], v[0:15]
	ds_read_b128 v[252:255], v228 offset:45056
	v_max_f32_e32 v114, v97, v97
	v_max_f32_e32 v115, v96, v96
	v_max_f32_e32 v114, v115, v114
	v_max3_f32 v114, v114, v98, v99
	s_waitcnt lgkmcnt(3)
	v_mfma_f32_32x32x16_bf16 v[32:47], v[240:243], v[88:91], v[32:47]
	s_waitcnt lgkmcnt(2)
	v_mfma_f32_32x32x16_bf16 v[48:63], v[244:247], v[88:91], v[48:63]
	v_max3_f32 v80, v114, v100, v101
	v_max3_f32 v80, v80, v102, v103
	v_max3_f32 v80, v80, v104, v105
	v_max3_f32 v80, v80, v106, v107
	v_max3_f32 v80, v80, v108, v109
	v_max3_f32 v80, v80, v110, v111
	ds_bpermute_b32 v81, v229, v80
	s_waitcnt lgkmcnt(2)
	v_mfma_f32_32x32x16_bf16 v[16:31], v[248:251], v[88:91], v[16:31]
	v_add_f32_e32 v82, v118, v113
	v_add_f32_e32 v82, v119, v82
	v_add_f32_e32 v230, v112, v82
	s_waitcnt lgkmcnt(0)
	v_max_f32_e32 v81, v81, v81
	v_max_f32_e32 v82, v80, v81
	v_mfma_f32_32x32x16_bf16 v[0:15], v[252:255], v[88:91], v[0:15]
	s_cbranch_scc0 .Lmla_ld_exit
	s_mov_b32 s8, s16
	v_cmp_lt_f32_e32 vcc, 0, v82
	s_cbranch_vccnz .LBB0_858_ld
	s_branch .LBB0_859_ld
.Lmla_ld_exit:
	s_waitcnt vmcnt(0)
	s_barrier
	s_branch .LBB0_875
